# small-tile GEMM (sample rows) K-loops of FFN-down L0 and QKV L1: first half-step fragment reads double-buffered per 32-deep chunk instead of one ds_read+wait per MFMA pair
# baseline (speedup 1.0000x reference)
; #define PG8_LAS __attribute__((address_space(3)))
;     ...
;         for (int st = 0; st < nst; st += 2) {
; #pragma unroll
;           for (int s2 = 0; s2 < 2; ++s2) {
;             PG8_LAS bf16_t* As = (PG8_LAS bf16_t*)(lds + s2 * BUFB); PG8_LAS bf16_t* Bs = As + 128 * LS;
; #pragma unroll
;             for (int j = 0; j < NA; ++j) *(PG8_LAS u32x4*)(As + lr * LS + (lp + j) * 8) = ra[s2][j];
; #pragma unroll
;             for (int j = 0; j < NB; ++j) *(PG8_LAS u32x4*)(Bs + lrb * LS + (lpb + j) * 8) = rb[s2][j];
;             __syncthreads();
;             if (st + 2 < nst) {
; #pragma unroll
;                 for (int j = 0; j < NA; ++j) ra[s2][j] = *(const u32x4*)(ga + 128 * (st + 2 + s2) + 8 * j);
; #pragma unroll
;                 for (int j = 0; j < NB; ++j) rb[s2][j] = *(const u32x4*)(gb + 128 * (st + 2 + s2) + 8 * j); }
;             if (active) {
; #pragma unroll
;             for (int kc = 0; kc < 4; ++kc) {
;                 bf16x8 af[4], bfr[2];
; #pragma unroll
;                 for (int m = 0; m < 4; ++m) af[m] = *(const PG8_LAS bf16x8*)(As + (64 * wr + 16 * m + fr) * LS + 32 * kc + 8 * fq);
; #pragma unroll
;                 for (int n = 0; n < 2; ++n) bfr[n] = *(const PG8_LAS bf16x8*)(Bs + (32 * wc + 8 * (fr >> 2) + 4 * n + (fr & 3)) * LS + 32 * kc + 8 * fq);
; #pragma unroll
;                 for (int m = 0; m < 4; ++m)
; #pragma unroll
;                     for (int n = 0; n < 2; ++n) acc[m][n] = __builtin_amdgcn_mfma_f32_16x16x32_bf16(bfr[n], af[m], acc[m][n], 0, 0, 0);
;             } }
.LBB0_1132:
	v_cndmask_b32_e64 v1, 0, 1, s[2:3]
	v_cmp_ne_u32_e64 s[0:1], 1, v1
	s_andn2_b64 vcc, exec, s[2:3]
	s_cbranch_vccnz .LBB0_1134
	v_add_u32_e32 v1, v88, v90
	v_add_u32_e32 v110, v88, v89
	ds_read_b128 v[130:133], v1 offset:34816
	ds_read_b128 v[134:137], v1 offset:35904
	ds_read_b128 v[138:141], v110
	ds_read_b128 v[142:145], v110 offset:4352
	ds_read_b128 v[146:149], v110 offset:8704
	ds_read_b128 v[150:153], v110 offset:13056
	ds_read_b128 v[154:157], v1 offset:34880
	ds_read_b128 v[158:161], v1 offset:35968
	ds_read_b128 v[162:165], v110 offset:64
	ds_read_b128 v[166:169], v110 offset:4416
	ds_read_b128 v[170:173], v110 offset:8768
	ds_read_b128 v[174:177], v110 offset:13120
	s_waitcnt lgkmcnt(6)
	v_mfma_f32_16x16x32_bf16 v[58:61], v[130:133], v[138:141], v[58:61]
	v_mfma_f32_16x16x32_bf16 v[62:65], v[134:137], v[138:141], v[62:65]
	v_mfma_f32_16x16x32_bf16 v[54:57], v[130:133], v[142:145], v[54:57]
	v_mfma_f32_16x16x32_bf16 v[50:53], v[134:137], v[142:145], v[50:53]
	v_mfma_f32_16x16x32_bf16 v[46:49], v[130:133], v[146:149], v[46:49]
	v_mfma_f32_16x16x32_bf16 v[42:45], v[134:137], v[146:149], v[42:45]
	v_mfma_f32_16x16x32_bf16 v[22:25], v[130:133], v[150:153], v[22:25]
	v_mfma_f32_16x16x32_bf16 v[2:5], v[134:137], v[150:153], v[2:5]
	ds_read_b128 v[130:133], v1 offset:34944
	ds_read_b128 v[134:137], v1 offset:36032
	ds_read_b128 v[138:141], v110 offset:128
	ds_read_b128 v[142:145], v110 offset:4480
	ds_read_b128 v[146:149], v110 offset:8832
	ds_read_b128 v[150:153], v110 offset:13184
	s_waitcnt lgkmcnt(6)
	v_mfma_f32_16x16x32_bf16 v[58:61], v[154:157], v[162:165], v[58:61]
	v_mfma_f32_16x16x32_bf16 v[62:65], v[158:161], v[162:165], v[62:65]
	v_mfma_f32_16x16x32_bf16 v[54:57], v[154:157], v[166:169], v[54:57]
	v_mfma_f32_16x16x32_bf16 v[50:53], v[158:161], v[166:169], v[50:53]
	v_mfma_f32_16x16x32_bf16 v[46:49], v[154:157], v[170:173], v[46:49]
	v_mfma_f32_16x16x32_bf16 v[42:45], v[158:161], v[170:173], v[42:45]
	v_mfma_f32_16x16x32_bf16 v[22:25], v[154:157], v[174:177], v[22:25]
	v_mfma_f32_16x16x32_bf16 v[2:5], v[158:161], v[174:177], v[2:5]
	ds_read_b128 v[154:157], v1 offset:35008
	ds_read_b128 v[158:161], v1 offset:36096
	ds_read_b128 v[162:165], v110 offset:192
	ds_read_b128 v[166:169], v110 offset:4544
	ds_read_b128 v[170:173], v110 offset:8896
	ds_read_b128 v[174:177], v110 offset:13248
	s_waitcnt lgkmcnt(6)
	v_mfma_f32_16x16x32_bf16 v[58:61], v[130:133], v[138:141], v[58:61]
	v_mfma_f32_16x16x32_bf16 v[62:65], v[134:137], v[138:141], v[62:65]
	v_mfma_f32_16x16x32_bf16 v[54:57], v[130:133], v[142:145], v[54:57]
	v_mfma_f32_16x16x32_bf16 v[50:53], v[134:137], v[142:145], v[50:53]
	v_mfma_f32_16x16x32_bf16 v[46:49], v[130:133], v[146:149], v[46:49]
	v_mfma_f32_16x16x32_bf16 v[42:45], v[134:137], v[146:149], v[42:45]
	v_mfma_f32_16x16x32_bf16 v[22:25], v[130:133], v[150:153], v[22:25]
	v_mfma_f32_16x16x32_bf16 v[2:5], v[134:137], v[150:153], v[2:5]
	s_waitcnt lgkmcnt(0)
	v_mfma_f32_16x16x32_bf16 v[58:61], v[154:157], v[162:165], v[58:61]
	v_mfma_f32_16x16x32_bf16 v[62:65], v[158:161], v[162:165], v[62:65]
	v_mfma_f32_16x16x32_bf16 v[54:57], v[154:157], v[166:169], v[54:57]
	v_mfma_f32_16x16x32_bf16 v[50:53], v[158:161], v[166:169], v[50:53]
	v_mfma_f32_16x16x32_bf16 v[46:49], v[154:157], v[170:173], v[46:49]
	v_mfma_f32_16x16x32_bf16 v[42:45], v[158:161], v[170:173], v[42:45]
	v_mfma_f32_16x16x32_bf16 v[22:25], v[154:157], v[174:177], v[22:25]
	v_mfma_f32_16x16x32_bf16 v[2:5], v[158:161], v[174:177], v[2:5]
.LBB0_1134:
	s_andn2_b64 vcc, exec, s[16:17]
	ds_write_b128 v93, v[10:13]
	ds_write_b128 v93, v[14:17] offset:16
	ds_write_b128 v94, v[18:21]
	ds_write_b128 v94, v[6:9] offset:16
	s_waitcnt lgkmcnt(0)
	s_barrier
	s_cbranch_vccnz .LBB0_1136
	s_mov_b64 s[16:17], 0x14000300
	v_add_co_u32_e32 v8, vcc, 0x14000000, v84
	v_lshl_add_u64 v[6:7], v[84:85], 0, s[16:17]
	s_nop 0
	v_addc_co_u32_e32 v9, vcc, 0, v85, vcc
	global_load_dwordx4 v[10:13], v[8:9], off offset:768
	global_load_dwordx4 v[14:17], v[6:7], off offset:16
	s_nop 0
	global_load_dwordx4 v[6:9], v[82:83], off offset:16
	global_load_dwordx4 v[18:21], v[82:83], off
	s_and_b64 vcc, exec, s[0:1]
	s_cbranch_vccnz .LBB0_1129
	s_branch .LBB0_1137
	s_nop 0
	s_nop 0
	s_nop 0
	s_nop 0
	s_nop 0
	s_nop 0
	s_nop 0
	s_nop 0
	s_nop 0
	s_nop 0
	s_nop 0
	s_nop 0

; #define PG8_LAS __attribute__((address_space(3)))
;     ...
;         for (int st = 0; st < nst; st += 2) {
; #pragma unroll
;           for (int s2 = 0; s2 < 2; ++s2) {
;             PG8_LAS bf16_t* As = (PG8_LAS bf16_t*)(lds + s2 * BUFB); PG8_LAS bf16_t* Bs = As + 128 * LS;
; #pragma unroll
;             for (int j = 0; j < NA; ++j) *(PG8_LAS u32x4*)(As + lr * LS + (lp + j) * 8) = ra[s2][j];
; #pragma unroll
;             for (int j = 0; j < NB; ++j) *(PG8_LAS u32x4*)(Bs + lrb * LS + (lpb + j) * 8) = rb[s2][j];
;             __syncthreads();
;             if (st + 2 < nst) {
; #pragma unroll
;                 for (int j = 0; j < NA; ++j) ra[s2][j] = *(const u32x4*)(ga + 128 * (st + 2 + s2) + 8 * j);
; #pragma unroll
;                 for (int j = 0; j < NB; ++j) rb[s2][j] = *(const u32x4*)(gb + 128 * (st + 2 + s2) + 8 * j); }
;             if (active) {
; #pragma unroll
;             for (int kc = 0; kc < 4; ++kc) {
;                 bf16x8 af[4], bfr[2];
; #pragma unroll
;                 for (int m = 0; m < 4; ++m) af[m] = *(const PG8_LAS bf16x8*)(As + (64 * wr + 16 * m + fr) * LS + 32 * kc + 8 * fq);
; #pragma unroll
;                 for (int n = 0; n < 2; ++n) bfr[n] = *(const PG8_LAS bf16x8*)(Bs + (32 * wc + 8 * (fr >> 2) + 4 * n + (fr & 3)) * LS + 32 * kc + 8 * fq);
; #pragma unroll
;                 for (int m = 0; m < 4; ++m)
; #pragma unroll
;                     for (int n = 0; n < 2; ++n) acc[m][n] = __builtin_amdgcn_mfma_f32_16x16x32_bf16(bfr[n], af[m], acc[m][n], 0, 0, 0);
;             } }
.LBB0_1226:
	v_cndmask_b32_e64 v1, 0, 1, s[2:3]
	v_cmp_ne_u32_e64 s[0:1], 1, v1
	s_andn2_b64 vcc, exec, s[2:3]
	s_cbranch_vccnz .LBB0_1228
	v_add_u32_e32 v1, v100, v102
	v_add_u32_e32 v122, v100, v101
	ds_read_b128 v[124:127], v1 offset:34816
	ds_read_b128 v[128:131], v1 offset:35904
	ds_read_b128 v[132:135], v122
	ds_read_b128 v[136:139], v122 offset:4352
	ds_read_b128 v[140:143], v122 offset:8704
	ds_read_b128 v[144:147], v122 offset:13056
	ds_read_b128 v[148:151], v1 offset:34880
	ds_read_b128 v[152:155], v1 offset:35968
	ds_read_b128 v[156:159], v122 offset:64
	ds_read_b128 v[160:163], v122 offset:4416
	ds_read_b128 v[164:167], v122 offset:8768
	ds_read_b128 v[168:171], v122 offset:13120
	s_waitcnt lgkmcnt(6)
	v_mfma_f32_16x16x32_bf16 v[78:81], v[124:127], v[132:135], v[78:81]
	v_mfma_f32_16x16x32_bf16 v[62:65], v[128:131], v[132:135], v[62:65]
	v_mfma_f32_16x16x32_bf16 v[50:53], v[124:127], v[136:139], v[50:53]
	v_mfma_f32_16x16x32_bf16 v[42:45], v[128:131], v[136:139], v[42:45]
	v_mfma_f32_16x16x32_bf16 v[26:29], v[124:127], v[140:143], v[26:29]
	v_mfma_f32_16x16x32_bf16 v[22:25], v[128:131], v[140:143], v[22:25]
	v_mfma_f32_16x16x32_bf16 v[66:69], v[124:127], v[144:147], v[66:69]
	v_mfma_f32_16x16x32_bf16 v[2:5], v[128:131], v[144:147], v[2:5]
	ds_read_b128 v[124:127], v1 offset:34944
	ds_read_b128 v[128:131], v1 offset:36032
	ds_read_b128 v[132:135], v122 offset:128
	ds_read_b128 v[136:139], v122 offset:4480
	ds_read_b128 v[140:143], v122 offset:8832
	ds_read_b128 v[144:147], v122 offset:13184
	s_waitcnt lgkmcnt(6)
	v_mfma_f32_16x16x32_bf16 v[78:81], v[148:151], v[156:159], v[78:81]
	v_mfma_f32_16x16x32_bf16 v[62:65], v[152:155], v[156:159], v[62:65]
	v_mfma_f32_16x16x32_bf16 v[50:53], v[148:151], v[160:163], v[50:53]
	v_mfma_f32_16x16x32_bf16 v[42:45], v[152:155], v[160:163], v[42:45]
	v_mfma_f32_16x16x32_bf16 v[26:29], v[148:151], v[164:167], v[26:29]
	v_mfma_f32_16x16x32_bf16 v[22:25], v[152:155], v[164:167], v[22:25]
	v_mfma_f32_16x16x32_bf16 v[66:69], v[148:151], v[168:171], v[66:69]
	v_mfma_f32_16x16x32_bf16 v[2:5], v[152:155], v[168:171], v[2:5]
	ds_read_b128 v[148:151], v1 offset:35008
	ds_read_b128 v[152:155], v1 offset:36096
	ds_read_b128 v[156:159], v122 offset:192
	ds_read_b128 v[160:163], v122 offset:4544
	ds_read_b128 v[164:167], v122 offset:8896
	ds_read_b128 v[168:171], v122 offset:13248
	s_waitcnt lgkmcnt(6)
	v_mfma_f32_16x16x32_bf16 v[78:81], v[124:127], v[132:135], v[78:81]
	v_mfma_f32_16x16x32_bf16 v[62:65], v[128:131], v[132:135], v[62:65]
	v_mfma_f32_16x16x32_bf16 v[50:53], v[124:127], v[136:139], v[50:53]
	v_mfma_f32_16x16x32_bf16 v[42:45], v[128:131], v[136:139], v[42:45]
	v_mfma_f32_16x16x32_bf16 v[26:29], v[124:127], v[140:143], v[26:29]
	v_mfma_f32_16x16x32_bf16 v[22:25], v[128:131], v[140:143], v[22:25]
	v_mfma_f32_16x16x32_bf16 v[66:69], v[124:127], v[144:147], v[66:69]
	v_mfma_f32_16x16x32_bf16 v[2:5], v[128:131], v[144:147], v[2:5]
	s_waitcnt lgkmcnt(0)
	v_mfma_f32_16x16x32_bf16 v[78:81], v[148:151], v[156:159], v[78:81]
	v_mfma_f32_16x16x32_bf16 v[62:65], v[152:155], v[156:159], v[62:65]
	v_mfma_f32_16x16x32_bf16 v[50:53], v[148:151], v[160:163], v[50:53]
	v_mfma_f32_16x16x32_bf16 v[42:45], v[152:155], v[160:163], v[42:45]
	v_mfma_f32_16x16x32_bf16 v[26:29], v[148:151], v[164:167], v[26:29]
	v_mfma_f32_16x16x32_bf16 v[22:25], v[152:155], v[164:167], v[22:25]
	v_mfma_f32_16x16x32_bf16 v[66:69], v[148:151], v[168:171], v[66:69]
	v_mfma_f32_16x16x32_bf16 v[2:5], v[152:155], v[168:171], v[2:5]
.LBB0_1228:
	s_andn2_b64 vcc, exec, s[16:17]
	s_waitcnt vmcnt(2)
	ds_write_b128 v105, v[34:37]
	ds_write_b128 v105, v[46:49] offset:16
	ds_write_b128 v105, v[38:41] offset:32
	ds_write_b128 v105, v[30:33] offset:48
	s_waitcnt vmcnt(0)
	ds_write_b128 v106, v[74:77]
	ds_write_b128 v106, v[70:73] offset:16
	s_waitcnt lgkmcnt(0)
	s_barrier
	s_cbranch_vccnz .LBB0_1230
	s_mov_b64 s[16:17], 0x4800300
	v_add_co_u32_e32 v30, vcc, 0x4800000, v96
	v_lshl_add_u64 v[46:47], v[96:97], 0, s[16:17]
	s_nop 0
	v_addc_co_u32_e32 v31, vcc, 0, v97, vcc
	global_load_dwordx4 v[34:37], v[30:31], off offset:768
	s_nop 0
	global_load_dwordx4 v[30:33], v[46:47], off offset:48
	global_load_dwordx4 v[38:41], v[46:47], off offset:32
	s_nop 0
	global_load_dwordx4 v[46:49], v[46:47], off offset:16
	s_nop 0
	global_load_dwordx4 v[70:73], v[94:95], off offset:16
	global_load_dwordx4 v[74:77], v[94:95], off
	s_and_b64 vcc, exec, s[0:1]
	s_cbranch_vccnz .LBB0_1223
	s_branch .LBB0_1231
	s_nop 0
	s_nop 0
	s_nop 0
	s_nop 0
	s_nop 0
	s_nop 0
	s_nop 0
	s_nop 0
	s_nop 0
	s_nop 0
	s_nop 0
	s_nop 0
